# P2/P3 reorder: conv-only P2 first, then half the workgroups run S5 tiles before the conv_out GEMM and half after it
# baseline (speedup 1.0000x reference)
_Z3fwd4Args:
	v_writelane_b32 v249, s0, 0
	v_writelane_b32 v249, s1, 1
	v_writelane_b32 v249, s2, 2
	v_mov_b32_e32 v250, v0
	s_and_b32 s101, s2, 3
	s_cmp_lg_u32 s101, 0
	s_cselect_b32 s101, 0x100, 0
	s_bfe_u32 s100, s2, 0x10001

.LBB0_337:
	s_cmp_lt_u32 s46, 0x40001
	s_mov_b64 s[42:43], 0
	s_cselect_b64 s[50:51], -1, 0
	s_and_b64 vcc, exec, s[50:51]
	s_cbranch_vccnz .LBB0_334
	s_branch .LBB0_330
.Lcls_tramp:
	s_branch .Lcls_top
.LBB0_338:
	s_andn2_b64 vcc, exec, s[42:43]
	s_cbranch_vccz .LBB0_342
	s_mov_b64 s[6:7], exec
	v_mbcnt_lo_u32_b32 v17, s6, 0
	v_mbcnt_hi_u32_b32 v17, s7, v17
	v_cmp_eq_u32_e32 vcc, 0, v17
	s_and_saveexec_b64 s[4:5], vcc
	s_cbranch_execz .LBB0_341
	s_bcnt1_i32_b64 s6, s[6:7]
	v_mov_b32_e32 v17, 0
	v_mov_b32_e32 v18, s6
	global_atomic_add v17, v18, s[2:3]

.LBB0_380:
	v_readlane_b32 s0, v248, 6
	v_readlane_b32 s2, v248, 8
	v_readlane_b32 s3, v248, 9
	s_add_u32 s70, s2, 0x1fe00000
	s_addc_u32 s71, s3, 0
	s_add_u32 s54, s2, 0x36600000
	s_addc_u32 s55, s3, 0
	v_readlane_b32 s1, v248, 7
	s_cmp_lt_i32 s4, 3
	s_cselect_b64 s[0:1], -1, 0
	s_cmp_gt_i32 s5, 2
	s_cselect_b64 s[2:3], -1, 0
	s_and_b64 s[0:1], s[0:1], s[2:3]
	s_andn2_b64 vcc, exec, s[0:1]
	s_cbranch_vccnz .LBB0_494
	s_bfe_u32 s98, s101, 0x80008
	s_cmp_eq_u32 s98, 0x10
	s_cbranch_scc1 .Lp2_ssm
	s_cmp_eq_u32 s98, 0x13
	s_cbranch_scc1 .Lp2_ssm
	s_branch .LBB0_403
.Lp2_ssm:
	s_mov_b64 s[0:1], s[96:97]
	s_load_dwordx2 s[72:73], s[0:1], 0x10
	s_mov_b64 s[0:1], s[96:97]
	s_load_dwordx2 s[74:75], s[0:1], 0x18
	v_readlane_b32 s1, v248, 0
	s_mul_i32 s0, s1, 0x4200
	s_add_i32 s2, s0, 0
	v_readlane_b32 s64, v248, 6
	s_mov_b32 s16, 0
	s_cmpk_gt_i32 s84, 0x1ff
	s_mul_i32 s3, s1, 0x54
	v_and_b32_e32 v207, 31, v0
	v_lshrrev_b32_e32 v1, 5, v206
	v_lshlrev_b32_e32 v208, 2, v206
	v_readlane_b32 s65, v248, 7
	v_readlane_b32 s66, v248, 8
	v_readlane_b32 s67, v248, 9
	s_cbranch_scc1 .LBB0_400
	s_cmpk_eq_i32 s95, 0x100
	s_cselect_b64 s[6:7], -1, 0
	s_lshl_b32 s0, s84, 4
	s_and_b32 s17, s0, 64
	s_ashr_i32 s0, s84, 3
	v_readlane_b32 s1, v248, 0
	s_add_i32 s17, s17, s0
	s_lshl_b32 s18, s1, 8
	s_lshl_b32 s28, s1, 9
	s_cmp_gt_i32 s1, 0
	s_cselect_b64 s[76:77], -1, 0
	s_cmp_eq_u32 s1, 7
	v_mov_b32_e32 v213, 0
	s_cselect_b64 s[78:79], -1, 0
	s_and_b32 s29, s1, 7
	v_add_lshl_u32 v210, s3, v206, 7
	v_mov_b32_e32 v211, v213
	v_lshlrev_b32_e32 v2, 4, v1
	s_cmp_gt_u32 s1, 7
	v_lshl_add_u64 v[214:215], s[54:55], 0, v[210:211]
	v_lshl_or_b32 v211, v207, 15, v2
	s_movk_i32 s0, 0x210
	v_add_u32_e32 v4, s2, v2
	v_and_b32_e32 v5, 32, v0
	v_mov_b32_e32 v2, s2
	s_cselect_b64 s[80:81], -1, 0
	s_and_b32 s34, s1, 0x7ffffff8
	v_mul_u32_u24_e32 v3, 0x210, v207
	v_add_u32_e32 v222, s2, v208
	v_mad_u32_u24 v6, v207, s0, v2
	v_add_u32_e32 v7, s2, v5
	v_lshlrev_b32_e32 v2, 2, v1
	s_cmp_lg_u32 s29, 0
	v_add_u32_e32 v8, 0, v208
	s_mov_b32 s11, 0x20000
	v_or_b32_e32 v209, s18, v206
	v_lshlrev_b32_e32 v220, 4, v206
	s_movk_i32 s19, 0x2000
	v_add_u32_e32 v221, 0x2000, v210
	v_lshlrev_b32_e32 v223, 3, v207
	v_add_u32_e32 v224, 0x21000, v8
	v_add_u32_e32 v225, 0x21100, v8
	s_mov_b32 s10, 0x100000
	s_movk_i32 s35, 0x1000
	s_movk_i32 s36, 0x3000
	s_movk_i32 s37, 0x4000
	s_movk_i32 s38, 0x5000
	s_movk_i32 s39, 0x6000
	s_movk_i32 s40, 0x7000
	s_mov_b32 s22, 0x15000
	s_mov_b32 s23, s11
	v_add_u32_e32 v226, v4, v3
	s_mov_b32 s41, 0x8000
	s_mov_b32 s42, 0x10000
	v_lshlrev_b32_e32 v216, 2, v206
	v_add_u32_e32 v227, v6, v5
	v_add_u32_e32 v228, v7, v3
	v_lshlrev_b32_e32 v212, 1, v2
	v_mov_b32_e32 v229, 0x15000
	v_add_u32_e32 v230, 32, v222
	v_add_u32_e32 v231, 48, v222
	v_add_u32_e32 v232, 64, v222
	v_add_u32_e32 v233, 0x50, v222
	v_add_u32_e32 v234, 0x60, v222
	v_add_u32_e32 v235, 0x70, v222
	v_add_u32_e32 v236, 0x80, v222
	v_add_u32_e32 v237, 0x90, v222
	v_add_u32_e32 v238, 0xa0, v222
	v_add_u32_e32 v239, 0xb0, v222
	v_add_u32_e32 v240, 0xc0, v222
	v_add_u32_e32 v241, 0xd0, v222
	v_add_u32_e32 v242, 0xe0, v222
	v_add_u32_e32 v243, 0xf0, v222
	v_add_u32_e32 v244, 16, v222
	s_mov_b32 s43, s84
	v_cmp_gt_u32_e64 s[4:5], 20, v206
	s_cselect_b64 s[82:83], -1, 0
	s_mov_b32 s26, 0x15000
	s_branch .LBB0_384

.LBB0_403:
	v_readlane_b32 s84, v248, 32
	v_readlane_b32 s82, v248, 37
	s_cmp_gt_i32 s84, 63
	v_readlane_b32 s66, v248, 30
	v_readlane_b32 s83, v248, 38
	v_readlane_b32 s67, v248, 31
	s_bfe_u32 s98, s101, 0x80008
	s_cmp_eq_u32 s98, 0x10
	s_cbranch_scc0 .Lp2_c1
	s_mov_b64 exec, -1
	s_movk_i32 s101, 0x1102
	s_waitcnt vmcnt(0) lgkmcnt(0)
	s_barrier
	v_readlane_b32 s4, v248, 4
	v_readlane_b32 s5, v248, 5
	s_branch .LBB0_494
.Lp2_c1:
	s_cmp_eq_u32 s98, 0x13
	s_cbranch_scc0 .Lp2_c2
	s_movk_i32 s101, 0x1403
	s_mov_b64 exec, -1
	v_readlane_b32 s0, v249, 0
	v_readlane_b32 s1, v249, 1
	v_readlane_b32 s2, v249, 2
	v_mov_b32_e32 v0, v250
	s_nop 4
	s_branch .Lcls_tramp
.Lp2_c2:
	s_cmp_gt_i32 s84, 63
	s_cbranch_scc0 .LBB0_440
	s_lshl_b32 s0, s84, 3
	v_readlane_b32 s1, v248, 0
	s_add_i32 s0, s0, s1
	s_lshl_b32 s0, s0, 6
	s_addk_i32 s0, 0x8000
	s_lshl_b32 s19, s95, 9
	v_or_b32_e32 v26, s0, v206
	s_mov_b32 s0, 0x240000
	s_mov_b64 s[2:3], s[96:97]
	s_mov_b64 s[6:7], s[96:97]
	s_add_i32 s18, s19, 0xffff8000
	v_cmp_gt_i32_e32 vcc, s0, v26
	s_and_saveexec_b64 s[0:1], vcc
	s_cbranch_execz .LBB0_427
	v_readfirstlane_b32 s4, v26
	s_load_dwordx2 s[10:11], s[2:3], 0x90
	v_and_b32_e32 v96, 0xff, v26
	v_lshlrev_b32_e32 v97, 5, v96
	v_lshlrev_b32_e32 v96, 4, v96
	v_add_u32_e32 v98, 0x2000, v97
	v_add_u32_e32 v99, 0x4000, v97
	s_lshr_b32 s4, s4, 8
	s_lshl_b32 s4, s4, 12
	v_readlane_b32 s8, v248, 45
	v_readlane_b32 s9, v248, 46
	v_readlane_b32 s12, v248, 49
	v_readlane_b32 s13, v248, 50
	s_nop 3
	s_add_u32 s20, s8, s4
	s_addc_u32 s21, s9, 0
	s_add_u32 s24, s12, s4
	s_addc_u32 s25, s13, 0
	s_add_u32 s26, s70, s4
	s_addc_u32 s27, s71, 0
	s_sub_u32 s22, s20, 0x2000
	s_subb_u32 s23, s21, 0
	s_waitcnt lgkmcnt(0)
	global_load_dwordx4 v[72:75], v97, s[10:11]
	global_load_dwordx4 v[76:79], v97, s[10:11] offset:16
	global_load_dwordx4 v[80:83], v98, s[10:11]
	global_load_dwordx4 v[84:87], v98, s[10:11] offset:16
	global_load_dwordx4 v[88:91], v99, s[10:11]
	global_load_dwordx4 v[92:95], v99, s[10:11] offset:16
	global_load_dwordx4 v[100:103], v96, s[20:21]
	global_load_dwordx4 v[104:107], v96, s[20:21] offset:-4096
	global_load_dwordx4 v[108:111], v96, s[22:23]
	global_load_dwordx4 v[112:115], v96, s[24:25]
	s_add_u32 s20, s20, 0x180000
	s_addc_u32 s21, s21, 0
	s_add_u32 s22, s22, 0x180000
	s_addc_u32 s23, s23, 0
	s_add_u32 s24, s24, 0x180000
	s_addc_u32 s25, s25, 0
	global_load_dwordx4 v[116:119], v96, s[20:21]
	global_load_dwordx4 v[120:123], v96, s[20:21] offset:-4096
	global_load_dwordx4 v[124:127], v96, s[22:23]
	global_load_dwordx4 v[128:131], v96, s[24:25]
	s_add_u32 s20, s20, 0x180000
	s_addc_u32 s21, s21, 0
	s_add_u32 s22, s22, 0x180000
	s_addc_u32 s23, s23, 0
	s_add_u32 s24, s24, 0x180000
	s_addc_u32 s25, s25, 0
	s_mov_b32 s28, 8

.LBB0_494:
	v_readlane_b32 s0, v248, 6
	v_readlane_b32 s2, v248, 8
	v_readlane_b32 s3, v248, 9
	s_add_u32 s62, s2, 0x3ae00000
	s_addc_u32 s63, s3, 0
	v_readlane_b32 s1, v248, 7
	s_cmp_lt_i32 s4, 4
	s_cselect_b64 s[0:1], -1, 0
	s_cmp_gt_i32 s5, 3
	s_cselect_b64 s[2:3], -1, 0
	s_and_b64 s[0:1], s[0:1], s[2:3]
	s_andn2_b64 vcc, exec, s[0:1]
	s_cbranch_vccnz .LBB0_602
	s_bfe_u32 s98, s101, 0x80008
	s_cmp_eq_u32 s98, 0x14
	s_cbranch_scc0 .Lp3_a
	s_and_b32 s101, s101, 0xff
	s_branch .LBB0_548
.Lp3_a:
	s_cmp_eq_u32 s98, 0x11
	s_cbranch_scc0 .Lp3_b
	s_and_b32 s101, s101, 0xff
	s_branch .Lp3_run
.Lp3_b:
	s_cmp_eq_u32 s100, 0
	s_cbranch_scc0 .Lp3_y
	s_movk_i32 s101, 0x1002
	s_mov_b64 exec, -1
	v_readlane_b32 s0, v249, 0
	v_readlane_b32 s1, v249, 1
	v_readlane_b32 s2, v249, 2
	v_mov_b32_e32 v0, v250
	s_nop 4
	s_branch .Lcls_tramp
.Lp3_y:
	s_or_b32 s101, s101, 0x1200
.Lp3_run:
	s_cmpk_gt_i32 s84, 0x1ff
	s_mov_b32 s42, 0
	s_cbranch_scc1 .LBB0_497
	s_abs_i32 s0, s95
	v_cvt_f32_u32_e32 v1, s0
	s_sub_i32 s1, s95, s84
	s_add_i32 s2, s1, 0x1ff
	s_sub_i32 s1, 0xfffffe01, s1
	v_rcp_iflag_f32_e32 v1, v1
	s_xor_b32 s4, s2, s95
	s_sub_i32 s3, 0, s0
	s_max_i32 s1, s2, s1
	v_mul_f32_e32 v1, 0x4f7ffffe, v1
	v_cvt_u32_f32_e32 v1, v1
	s_ashr_i32 s2, s4, 31
	v_readfirstlane_b32 s4, v1
	s_mul_i32 s3, s3, s4
	s_mul_hi_u32 s3, s4, s3
	s_add_i32 s4, s4, s3
	s_mul_hi_u32 s3, s1, s4
	s_mul_i32 s4, s3, s0
	s_sub_i32 s1, s1, s4
	s_add_i32 s5, s3, 1
	s_sub_i32 s4, s1, s0
	s_cmp_ge_u32 s1, s0
	s_cselect_b32 s3, s5, s3
	s_cselect_b32 s1, s4, s1
	s_add_i32 s4, s3, 1
	s_cmp_ge_u32 s1, s0
	s_cselect_b32 s0, s4, s3
	s_xor_b32 s0, s0, s2
	s_sub_i32 s42, s0, s2

.LBB0_548:
	s_bfe_u32 s98, s101, 0x80008
	s_cmp_eq_u32 s98, 0x12
	s_cbranch_scc0 .Lp3_e
	s_movk_i32 s101, 0x1302
	s_mov_b64 exec, -1
	v_readlane_b32 s0, v249, 0
	v_readlane_b32 s1, v249, 1
	v_readlane_b32 s2, v249, 2
	v_mov_b32_e32 v0, v250
	s_nop 4
	s_branch .Lcls_tramp
